# v47 + s_setprio 2 over the non-MFMA part of the in-proj K step (wait, poll, fragment reads, DMA issue), back to 0 for the MFMA block
# speedup vs baseline: 1.0047x; 1.0047x over previous
.Lgin_k:
	s_setprio 2
	s_waitcnt vmcnt(0)
	s_barrier
	v_and_b32_e32 v128, 63, v193
	v_and_b32_e32 v129, 15, v193
	v_lshlrev_b32_e32 v128, 7, v128
	v_lshl_add_u32 v128, v129, 2, v128
	v_add_u32_e32 v129, 8192, v128
	v_add_u32_e32 v130, 16384, v128
	v_add_u32_e32 v131, 24576, v128
	v_add_u32_e32 v132, 32768, v128
	v_add_u32_e32 v133, 40960, v128
	s_mov_b32 s28, 64

.Lgin_nodma:
	s_setprio 0
	v_mfma_f32_32x32x16_bf16 v[0:15], v[216:219], v[128:131], v[0:15]
	v_mfma_f32_32x32x16_bf16 v[16:31], v[232:235], v[128:131], v[16:31]
	v_mfma_f32_32x32x16_bf16 v[32:47], v[216:219], v[148:151], v[32:47]
	v_mfma_f32_32x32x16_bf16 v[48:63], v[232:235], v[148:151], v[48:63]
	v_mfma_f32_32x32x16_bf16 v[64:79], v[216:219], v[164:167], v[64:79]
	v_mfma_f32_32x32x16_bf16 v[80:95], v[232:235], v[164:167], v[80:95]
	v_mfma_f32_32x32x16_bf16 v[96:111], v[216:219], v[180:183], v[96:111]
	v_mfma_f32_32x32x16_bf16 v[112:127], v[232:235], v[180:183], v[112:127]
	v_mfma_f32_32x32x16_bf16 v[0:15], v[220:223], v[132:135], v[0:15]
	v_mfma_f32_32x32x16_bf16 v[16:31], v[236:239], v[132:135], v[16:31]
	v_mfma_f32_32x32x16_bf16 v[32:47], v[220:223], v[152:155], v[32:47]
	v_mfma_f32_32x32x16_bf16 v[48:63], v[236:239], v[152:155], v[48:63]
	v_mfma_f32_32x32x16_bf16 v[64:79], v[220:223], v[168:171], v[64:79]
	v_mfma_f32_32x32x16_bf16 v[80:95], v[236:239], v[168:171], v[80:95]
	v_mfma_f32_32x32x16_bf16 v[96:111], v[220:223], v[184:187], v[96:111]
	v_mfma_f32_32x32x16_bf16 v[112:127], v[236:239], v[184:187], v[112:127]
	v_mfma_f32_32x32x16_bf16 v[0:15], v[224:227], v[136:139], v[0:15]
	v_mfma_f32_32x32x16_bf16 v[16:31], v[240:243], v[136:139], v[16:31]
	v_mfma_f32_32x32x16_bf16 v[32:47], v[224:227], v[156:159], v[32:47]
	v_mfma_f32_32x32x16_bf16 v[48:63], v[240:243], v[156:159], v[48:63]
	v_mfma_f32_32x32x16_bf16 v[64:79], v[224:227], v[172:175], v[64:79]
	v_mfma_f32_32x32x16_bf16 v[80:95], v[240:243], v[172:175], v[80:95]
	v_mfma_f32_32x32x16_bf16 v[96:111], v[224:227], v[188:191], v[96:111]
	v_mfma_f32_32x32x16_bf16 v[112:127], v[240:243], v[188:191], v[112:127]
	v_mfma_f32_32x32x16_bf16 v[0:15], v[228:231], v[140:143], v[0:15]
	v_mfma_f32_32x32x16_bf16 v[16:31], v[244:247], v[140:143], v[16:31]
	v_mfma_f32_32x32x16_bf16 v[32:47], v[228:231], v[160:163], v[32:47]
	v_mfma_f32_32x32x16_bf16 v[48:63], v[244:247], v[160:163], v[48:63]
	v_mfma_f32_32x32x16_bf16 v[64:79], v[228:231], v[176:179], v[64:79]
	v_mfma_f32_32x32x16_bf16 v[80:95], v[244:247], v[176:179], v[80:95]
	v_mfma_f32_32x32x16_bf16 v[96:111], v[228:231], v[212:215], v[96:111]
	v_mfma_f32_32x32x16_bf16 v[112:127], v[244:247], v[212:215], v[112:127]
	s_sub_u32 s16, s16, 1
	s_cmp_lg_u32 s16, 0
	s_cbranch_scc1 .Lgin_k
	s_nop 15
	s_nop 3
	v_and_b32_e32 v215, 31, v193
	v_mul_u32_u24_e32 v212, 0x110, v215
	v_bfe_u32 v215, v193, 5, 1
	v_lshl_add_u32 v212, v215, 3, v212
	v_bfe_u32 v215, v193, 7, 1
	v_mov_b32_e32 v216, 34816
	v_mad_u32_u24 v212, v215, v216, v212
	v_bfe_u32 v215, v193, 6, 1
	v_lshl_add_u32 v212, v215, 7, v212
	v_cvt_pk_bf16_f32 v128, v0, v1
	v_cvt_pk_bf16_f32 v129, v2, v3
	ds_write_b64 v212, v[128:129] offset:0
	v_cvt_pk_bf16_f32 v130, v4, v5
	v_cvt_pk_bf16_f32 v131, v6, v7
	ds_write_b64 v212, v[130:131] offset:16
	v_cvt_pk_bf16_f32 v132, v8, v9
	v_cvt_pk_bf16_f32 v133, v10, v11
	ds_write_b64 v212, v[132:133] offset:32
	v_cvt_pk_bf16_f32 v134, v12, v13
	v_cvt_pk_bf16_f32 v135, v14, v15
	ds_write_b64 v212, v[134:135] offset:48
	v_cvt_pk_bf16_f32 v136, v16, v17
	v_cvt_pk_bf16_f32 v137, v18, v19
	ds_write_b64 v212, v[136:137] offset:64
	v_cvt_pk_bf16_f32 v138, v20, v21
	v_cvt_pk_bf16_f32 v139, v22, v23
	ds_write_b64 v212, v[138:139] offset:80
	v_cvt_pk_bf16_f32 v140, v24, v25
	v_cvt_pk_bf16_f32 v141, v26, v27
	ds_write_b64 v212, v[140:141] offset:96
	v_cvt_pk_bf16_f32 v142, v28, v29
	v_cvt_pk_bf16_f32 v143, v30, v31
	ds_write_b64 v212, v[142:143] offset:112
	v_cvt_pk_bf16_f32 v128, v32, v33
	v_cvt_pk_bf16_f32 v129, v34, v35
	ds_write_b64 v212, v[128:129] offset:8704
	v_cvt_pk_bf16_f32 v130, v36, v37
	v_cvt_pk_bf16_f32 v131, v38, v39
	ds_write_b64 v212, v[130:131] offset:8720
	v_cvt_pk_bf16_f32 v132, v40, v41
	v_cvt_pk_bf16_f32 v133, v42, v43
	ds_write_b64 v212, v[132:133] offset:8736
	v_cvt_pk_bf16_f32 v134, v44, v45
	v_cvt_pk_bf16_f32 v135, v46, v47
	ds_write_b64 v212, v[134:135] offset:8752
	v_cvt_pk_bf16_f32 v136, v48, v49
	v_cvt_pk_bf16_f32 v137, v50, v51
	ds_write_b64 v212, v[136:137] offset:8768
	v_cvt_pk_bf16_f32 v138, v52, v53
	v_cvt_pk_bf16_f32 v139, v54, v55
	ds_write_b64 v212, v[138:139] offset:8784
	v_cvt_pk_bf16_f32 v140, v56, v57
	v_cvt_pk_bf16_f32 v141, v58, v59
	ds_write_b64 v212, v[140:141] offset:8800
	v_cvt_pk_bf16_f32 v142, v60, v61
	v_cvt_pk_bf16_f32 v143, v62, v63
	ds_write_b64 v212, v[142:143] offset:8816
	v_cvt_pk_bf16_f32 v128, v64, v65
	v_cvt_pk_bf16_f32 v129, v66, v67
	ds_write_b64 v212, v[128:129] offset:17408
	v_cvt_pk_bf16_f32 v130, v68, v69
	v_cvt_pk_bf16_f32 v131, v70, v71
	ds_write_b64 v212, v[130:131] offset:17424
	v_cvt_pk_bf16_f32 v132, v72, v73
	v_cvt_pk_bf16_f32 v133, v74, v75
	ds_write_b64 v212, v[132:133] offset:17440
	v_cvt_pk_bf16_f32 v134, v76, v77
	v_cvt_pk_bf16_f32 v135, v78, v79
	ds_write_b64 v212, v[134:135] offset:17456
	v_cvt_pk_bf16_f32 v136, v80, v81
	v_cvt_pk_bf16_f32 v137, v82, v83
	ds_write_b64 v212, v[136:137] offset:17472
	v_cvt_pk_bf16_f32 v138, v84, v85
	v_cvt_pk_bf16_f32 v139, v86, v87
	ds_write_b64 v212, v[138:139] offset:17488
	v_cvt_pk_bf16_f32 v140, v88, v89
	v_cvt_pk_bf16_f32 v141, v90, v91
	ds_write_b64 v212, v[140:141] offset:17504
	v_cvt_pk_bf16_f32 v142, v92, v93
	v_cvt_pk_bf16_f32 v143, v94, v95
	ds_write_b64 v212, v[142:143] offset:17520
	v_cvt_pk_bf16_f32 v128, v96, v97
	v_cvt_pk_bf16_f32 v129, v98, v99
	ds_write_b64 v212, v[128:129] offset:26112
	v_cvt_pk_bf16_f32 v130, v100, v101
	v_cvt_pk_bf16_f32 v131, v102, v103
	ds_write_b64 v212, v[130:131] offset:26128
	v_cvt_pk_bf16_f32 v132, v104, v105
	v_cvt_pk_bf16_f32 v133, v106, v107
	ds_write_b64 v212, v[132:133] offset:26144
	v_cvt_pk_bf16_f32 v134, v108, v109
	v_cvt_pk_bf16_f32 v135, v110, v111
	ds_write_b64 v212, v[134:135] offset:26160
	v_cvt_pk_bf16_f32 v136, v112, v113
	v_cvt_pk_bf16_f32 v137, v114, v115
	ds_write_b64 v212, v[136:137] offset:26176
	v_cvt_pk_bf16_f32 v138, v116, v117
	v_cvt_pk_bf16_f32 v139, v118, v119
	ds_write_b64 v212, v[138:139] offset:26192
	v_cvt_pk_bf16_f32 v140, v120, v121
	v_cvt_pk_bf16_f32 v141, v122, v123
	ds_write_b64 v212, v[140:141] offset:26208
	v_cvt_pk_bf16_f32 v142, v124, v125
	v_cvt_pk_bf16_f32 v143, v126, v127
	ds_write_b64 v212, v[142:143] offset:26224
	s_waitcnt lgkmcnt(0)
	s_barrier
	v_lshrrev_b32_e32 v215, 4, v193
	v_and_b32_e32 v216, 15, v193
	v_mul_u32_u24_e32 v213, 0x110, v215
	v_lshl_add_u32 v213, v216, 4, v213
	v_mul_lo_u32 v214, v215, s12
	v_lshl_add_u32 v214, v216, 4, v214
	s_lshl_b32 s28, s12, 4
	ds_read_b128 v[148:151], v213 offset:0
	ds_read_b128 v[152:155], v213 offset:4352
	ds_read_b128 v[156:159], v213 offset:8704
	ds_read_b128 v[160:163], v213 offset:13056
	ds_read_b128 v[164:167], v213 offset:17408
	ds_read_b128 v[168:171], v213 offset:21760
	ds_read_b128 v[172:175], v213 offset:26112
	ds_read_b128 v[176:179], v213 offset:30464
	ds_read_b128 v[180:183], v213 offset:34816
	ds_read_b128 v[184:187], v213 offset:39168
	ds_read_b128 v[188:191], v213 offset:43520
	ds_read_b128 v[220:223], v213 offset:47872
	ds_read_b128 v[224:227], v213 offset:52224
	ds_read_b128 v[228:231], v213 offset:56576
	ds_read_b128 v[232:235], v213 offset:60928
	ds_read_b128 v[236:239], v213 offset:65280
	s_waitcnt lgkmcnt(15)
	global_store_dwordx4 v214, v[148:151], s[26:27]
	s_add_u32 s26, s26, s28
	s_addc_u32 s27, s27, 0
	s_waitcnt lgkmcnt(14)
	global_store_dwordx4 v214, v[152:155], s[26:27]
	s_add_u32 s26, s26, s28
	s_addc_u32 s27, s27, 0
	s_waitcnt lgkmcnt(13)
	global_store_dwordx4 v214, v[156:159], s[26:27]
	s_add_u32 s26, s26, s28
	s_addc_u32 s27, s27, 0
	s_waitcnt lgkmcnt(12)
	global_store_dwordx4 v214, v[160:163], s[26:27]
	s_add_u32 s26, s26, s28
	s_addc_u32 s27, s27, 0
	s_waitcnt lgkmcnt(11)
	global_store_dwordx4 v214, v[164:167], s[26:27]
	s_add_u32 s26, s26, s28
	s_addc_u32 s27, s27, 0
	s_waitcnt lgkmcnt(10)
	global_store_dwordx4 v214, v[168:171], s[26:27]
	s_add_u32 s26, s26, s28
	s_addc_u32 s27, s27, 0
	s_waitcnt lgkmcnt(9)
	global_store_dwordx4 v214, v[172:175], s[26:27]
	s_add_u32 s26, s26, s28
	s_addc_u32 s27, s27, 0
	s_waitcnt lgkmcnt(8)
	global_store_dwordx4 v214, v[176:179], s[26:27]
	s_add_u32 s26, s26, s28
	s_addc_u32 s27, s27, 0
	s_waitcnt lgkmcnt(7)
	global_store_dwordx4 v214, v[180:183], s[26:27]
	s_add_u32 s26, s26, s28
	s_addc_u32 s27, s27, 0
	s_waitcnt lgkmcnt(6)
	global_store_dwordx4 v214, v[184:187], s[26:27]
	s_add_u32 s26, s26, s28
	s_addc_u32 s27, s27, 0
	s_waitcnt lgkmcnt(5)
	global_store_dwordx4 v214, v[188:191], s[26:27]
	s_add_u32 s26, s26, s28
	s_addc_u32 s27, s27, 0
	s_waitcnt lgkmcnt(4)
	global_store_dwordx4 v214, v[220:223], s[26:27]
	s_add_u32 s26, s26, s28
	s_addc_u32 s27, s27, 0
	s_waitcnt lgkmcnt(3)
	global_store_dwordx4 v214, v[224:227], s[26:27]
	s_add_u32 s26, s26, s28
	s_addc_u32 s27, s27, 0
	s_waitcnt lgkmcnt(2)
	global_store_dwordx4 v214, v[228:231], s[26:27]
	s_add_u32 s26, s26, s28
	s_addc_u32 s27, s27, 0
	s_waitcnt lgkmcnt(1)
	global_store_dwordx4 v214, v[232:235], s[26:27]
	s_add_u32 s26, s26, s28
	s_addc_u32 s27, s27, 0
	s_waitcnt lgkmcnt(0)
	global_store_dwordx4 v214, v[236:239], s[26:27]
	s_barrier
	s_add_u32 s0, s0, s6
	s_cmp_lt_u32 s0, s1
	s_cbranch_scc1 .Lgin_tile
	v_mov_b32_e32 v145, 0
